# static s_setprio 1 for waves 0-3 over the whole kernel (older GEMM half), no P7-exit drop
# speedup vs baseline: 1.0074x; 1.0074x over previous
_Z3fwd4Args:
	s_mov_b32 s86, s2
	s_load_dwordx8 s[60:67], s[0:1], 0x80
	s_load_dword s88, s[0:1], 0xc0
	s_load_dwordx4 s[80:83], s[0:1], 0xa0
	s_load_dwordx2 s[70:71], s[0:1], 0xb0
	s_add_u32 s2, s0, 0xc0
	s_addc_u32 s3, s1, 0
	v_readfirstlane_b32 s87, v0
	s_nop 3
	s_cmp_ge_u32 s87, 0x100
	s_cbranch_scc1 .Lstatic_prio_skip
	s_setprio 1
